# v33 plus: prologue modv and gate-weight stores write-through (sc1) and drained, so the prologue grid sync drops its 256 per-workgroup L2 write-backs
# speedup vs baseline: 1.0125x; 1.0021x over previous
; __device__ void prologue_phase(const Params& p, char* smem) {
;     ...
;       for (int i = threadIdx.x; i < 16 * 1024; i += NTHR) {
;         const int n = i & 15, k = i >> 4;
;         p.wg[(size_t)(l * 16 + n) * DM + k] = p.w_in[(size_t)l * DM * INW + (size_t)k * INW + 2304 + n];
;       }
.LBB0_40:
	global_load_dword v7, v[4:5], off
	s_mov_b64 s[4:5], 0x70800
	v_add_u32_e32 v6, 0x200, v6
	v_lshl_add_u64 v[4:5], v[4:5], 0, s[4:5]
	s_movk_i32 s4, 0x3dff
	v_cmp_lt_u32_e32 vcc, s4, v6
	s_mov_b64 s[4:5], 0x80
	s_or_b64 s[2:3], vcc, s[2:3]
	s_waitcnt vmcnt(0)
	global_store_dword v[2:3], v7, off sc1
	v_lshl_add_u64 v[2:3], v[2:3], 0, s[4:5]
	s_andn2_b64 exec, exec, s[2:3]
	s_cbranch_execnz .LBB0_40
	s_or_b64 exec, exec, s[2:3]

; __device__ void mod_job(const Params& p, int job, char* smem) {
;     ...
;   for (int i = tid; i < 17 * 64; i += NTHR) {
;     const int r = i >> 6, cc = i & 63;
;     float s = p.b_mod[l * 6144 + n0 + cc];
; #pragma unroll
;     for (int q = 0; q < 8; ++q) s += red[(q * 17 + r) * 64 + cc];
;     const int n = n0 + cc;
;     p.modv[((size_t)(l * 17 + r) * 6 + (n >> 10)) * DM + (n & 1023)] = s;
;   }
.LBB0_51:
	global_load_dword v5, v[2:3], off
	v_ashrrev_i32_e32 v8, 6, v82
	v_add_u32_e32 v9, 0x200, v82
	s_movk_i32 s9, 0x23f
	v_lshl_add_u32 v14, v8, 8, v4
	v_cmp_lt_i32_e32 vcc, s9, v82
	v_add_u32_e32 v16, s8, v8
	v_mov_b32_e32 v82, v9
	ds_read2st64_b32 v[8:9], v14 offset1:17
	ds_read2st64_b32 v[10:11], v14 offset0:34 offset1:51
	ds_read2st64_b32 v[12:13], v14 offset0:68 offset1:85
	ds_read2st64_b32 v[14:15], v14 offset0:102 offset1:119
	v_mad_i64_i32 v[16:17], s[10:11], v16, 6, s[6:7]
	v_lshlrev_b64 v[16:17], 12, v[16:17]
	s_or_b64 s[4:5], vcc, s[4:5]
	v_lshl_add_u64 v[16:17], v[6:7], 0, v[16:17]
	s_waitcnt vmcnt(0) lgkmcnt(3)
	v_add_f32_e32 v5, v5, v8
	v_add_f32_e32 v5, v5, v9
	s_waitcnt lgkmcnt(2)
	v_add_f32_e32 v5, v5, v10
	v_add_f32_e32 v5, v5, v11
	s_waitcnt lgkmcnt(1)
	v_add_f32_e32 v5, v5, v12
	v_add_f32_e32 v5, v5, v13
	s_waitcnt lgkmcnt(0)
	v_add_f32_e32 v5, v5, v14
	v_add_f32_e32 v5, v5, v15
	global_store_dword v[16:17], v5, off sc1
	s_andn2_b64 exec, exec, s[4:5]
	s_cbranch_execnz .LBB0_51

; __device__ void mixer_phase(const Params& p, int layer, char* smem) {
;     ...
;     if (threadIdx.x == 0) *slot = atomicAdd(ctr, 1u);
; __global__ void __launch_bounds__(NTHR) fwd_megakernel(Params p) {
;     ...
;   prologue_phase(p, smem_raw);
;   grid.sync();
.LBB0_55:
	s_load_dwordx2 s[76:77], s[0:1], 0x140
	v_lshrrev_b32_e32 v1, 20, v0
	v_lshrrev_b32_e32 v0, 10, v0
	v_or_b32_e32 v0, v0, v1
	s_movk_i32 s0, 0x3ff
	v_and_or_b32 v0, v0, s0, v234
	v_cmp_eq_u32_e32 vcc, 0, v0
	s_waitcnt vmcnt(0) lgkmcnt(0)
	s_barrier
	s_and_saveexec_b64 s[0:1], vcc
	s_cbranch_execz .LBB0_65
	s_waitcnt vmcnt(0)
	s_load_dwordx2 s[2:3], s[28:29], 0x58
	v_mov_b32_e32 v2, 0
	s_mov_b64 s[4:5], exec
	v_mbcnt_lo_u32_b32 v1, s4, 0
	v_mbcnt_hi_u32_b32 v1, s5, v1
	s_waitcnt lgkmcnt(0)
	global_load_dword v0, v2, s[2:3] offset:40
	v_cmp_eq_u32_e32 vcc, 0, v1
	s_and_saveexec_b64 s[6:7], vcc
	s_cbranch_execz .LBB0_58
	s_bcnt1_i32_b64 s4, s[4:5]
	v_mov_b32_e32 v3, s4
	global_atomic_add v3, v2, v3, s[2:3] offset:32 sc0
